# v7 + grid-barrier acquire (L1 invalidate) issued at arrival instead of after the release is observed: its latency overlaps the wait; no loads of other workgroups' fresh data happen in between
# speedup vs baseline: 1.0118x; 1.0054x over previous
.LBB0_29:
	s_waitcnt vmcnt(0)
	s_barrier
	s_mov_b64 s[4:5], exec
	v_readlane_b32 s6, v250, 4
	v_readlane_b32 s7, v250, 5
	s_and_b64 s[6:7], s[4:5], s[6:7]
	s_mov_b64 exec, s[6:7]
	s_cbranch_execz .LBB0_53
	s_add_i32 s3, 0, 0x22fc0
	v_mov_b32_e32 v0, s3
	s_waitcnt vmcnt(0) expcnt(0) lgkmcnt(0)
	buffer_inv sc1
	ds_read_b32 v1, v0
	s_add_i32 s3, 0, 0x22fc4
	v_mov_b32_e32 v0, s3
	ds_read_b32 v0, v0
	s_waitcnt lgkmcnt(1)
	v_cmp_ne_u32_e32 vcc, 0, v1
	s_cbranch_vccnz .LBB0_45
	s_add_u32 s6, s68, 0x14200
	s_addc_u32 s7, s69, 0
	s_add_u32 s8, s68, 0x14400
	s_addc_u32 s9, s69, 0
	s_add_u32 s10, s68, 0x14500
	s_addc_u32 s11, s69, 0
	s_add_u32 s16, s68, 0x14600
	s_addc_u32 s17, s69, 0
	s_add_u32 s18, s68, 0x14700
	s_addc_u32 s19, s69, 0
	s_add_u32 s20, s68, 0x14800
	s_addc_u32 s21, s69, 0
	s_add_u32 s22, s68, 0x14900
	s_addc_u32 s23, s69, 0
	s_add_u32 s24, s68, 0x14a00
	s_addc_u32 s25, s69, 0
	s_load_dword s3, s[0:1], 0xd8
	s_add_u32 s26, s68, 0x14b00
	s_addc_u32 s27, s69, 0
	s_add_u32 s28, s68, 0x14c00
	s_addc_u32 s29, s69, 0
	s_add_u32 s30, s68, 0x14d00
	s_waitcnt lgkmcnt(0)
	s_mul_i32 s3, s39, s3
	s_addc_u32 s31, s69, 0
	s_mul_i32 s3, s3, s38
	s_add_u32 s38, s68, 0x14e00
	s_addc_u32 s39, s69, 0
	s_add_u32 s42, s68, 0x14f00
	s_addc_u32 s43, s69, 0
	s_add_u32 s44, s68, 0x15000
	s_addc_u32 s45, s69, 0
	s_add_u32 s46, s68, 0x15100
	s_addc_u32 s47, s69, 0
	s_add_u32 s72, s68, 0x15200
	s_addc_u32 s73, s69, 0
	s_add_u32 s78, s68, 0x15300
	s_addc_u32 s79, s69, 0
	s_mov_b32 s52, 1
	v_mov_b32_e32 v16, 0
	s_branch .LBB0_33

.LBB0_84:
	s_waitcnt vmcnt(0)
	s_nop 0
	s_waitcnt vmcnt(0)

.LBB0_91:
	s_waitcnt vmcnt(0)
	s_barrier
	s_mov_b64 s[0:1], exec
	v_readlane_b32 s4, v250, 4
	v_readlane_b32 s5, v250, 5
	v_readlane_b32 s6, v250, 38
	s_and_b64 s[4:5], s[0:1], s[4:5]
	v_readlane_b32 s7, v250, 39
	s_mov_b64 exec, s[4:5]
	s_cbranch_execz .LBB0_115
	s_add_i32 s3, 0, 0x22fc0
	v_mov_b32_e32 v0, s3
	s_waitcnt vmcnt(0) expcnt(0) lgkmcnt(0)
	buffer_inv sc1
	ds_read_b32 v1, v0
	s_add_i32 s3, 0, 0x22fc4
	v_mov_b32_e32 v0, s3
	ds_read_b32 v0, v0
	s_waitcnt lgkmcnt(1)
	v_cmp_ne_u32_e32 vcc, 0, v1
	s_cbranch_vccnz .LBB0_107
	s_mul_i32 s3, s7, s6
	v_readlane_b32 s4, v250, 0
	s_mul_i32 s3, s3, s4
	s_add_u32 s4, s68, 0x14200
	s_addc_u32 s5, s69, 0
	s_add_u32 s6, s68, 0x14400
	s_addc_u32 s7, s69, 0
	s_add_u32 s8, s68, 0x14500
	s_addc_u32 s9, s69, 0
	s_add_u32 s10, s68, 0x14600
	s_addc_u32 s11, s69, 0
	s_add_u32 s38, s68, 0x14700
	s_addc_u32 s39, s69, 0
	s_add_u32 s40, s68, 0x14800
	s_addc_u32 s41, s69, 0
	s_add_u32 s44, s68, 0x14900
	s_addc_u32 s45, s69, 0
	s_add_u32 s46, s68, 0x14a00
	s_addc_u32 s47, s69, 0
	s_add_u32 s48, s68, 0x14b00
	s_addc_u32 s49, s69, 0
	s_add_u32 s82, s68, 0x14c00
	s_addc_u32 s83, s69, 0
	s_add_u32 s84, s68, 0x14d00
	s_addc_u32 s85, s69, 0
	s_add_u32 s86, s68, 0x14e00
	s_addc_u32 s87, s69, 0
	s_add_u32 s88, s68, 0x14f00
	s_addc_u32 s89, s69, 0
	s_add_u32 s90, s68, 0x15000
	s_addc_u32 s91, s69, 0
	s_add_u32 s92, s68, 0x15100
	s_addc_u32 s93, s69, 0
	s_add_u32 s72, s68, 0x15200
	s_addc_u32 s73, s69, 0
	s_add_u32 s94, s68, 0x15300
	s_addc_u32 s95, s69, 0
	s_mov_b32 s52, 1
	v_mov_b32_e32 v16, 0
	s_branch .LBB0_95

.LBB0_428:
	s_waitcnt vmcnt(0)
	s_waitcnt vmcnt(0)
	s_barrier
	s_mov_b64 s[0:1], exec
	v_readlane_b32 s4, v250, 4
	v_readlane_b32 s5, v250, 5
	s_and_b64 s[4:5], s[0:1], s[4:5]
	s_mov_b64 exec, s[4:5]
	s_cbranch_execz .LBB0_452
	s_add_i32 s3, 0, 0x22fc0
	v_mov_b32_e32 v0, s3
	s_waitcnt vmcnt(0) expcnt(0) lgkmcnt(0)
	buffer_inv sc1
	ds_read_b32 v1, v0
	s_add_i32 s3, 0, 0x22fc4
	v_mov_b32_e32 v0, s3
	ds_read_b32 v0, v0
	s_waitcnt lgkmcnt(1)
	v_cmp_ne_u32_e32 vcc, 0, v1
	s_cbranch_vccnz .LBB0_444
	s_add_u32 s4, s68, 0x14200
	s_addc_u32 s5, s69, 0
	s_add_u32 s6, s68, 0x14400
	s_addc_u32 s7, s69, 0
	s_add_u32 s8, s68, 0x14500
	s_addc_u32 s9, s69, 0
	s_add_u32 s10, s68, 0x14600
	s_addc_u32 s11, s69, 0
	s_add_u32 s14, s68, 0x14700
	s_addc_u32 s15, s69, 0
	s_add_u32 s46, s68, 0x14800
	s_addc_u32 s47, s69, 0
	s_add_u32 s48, s68, 0x14900
	s_addc_u32 s49, s69, 0
	s_add_u32 s54, s68, 0x14a00
	s_addc_u32 s55, s69, 0
	s_add_u32 s82, s68, 0x14b00
	s_addc_u32 s83, s69, 0
	s_add_u32 s84, s68, 0x14c00
	s_addc_u32 s85, s69, 0
	s_add_u32 s86, s68, 0x14d00
	s_addc_u32 s87, s69, 0
	s_add_u32 s88, s68, 0x14e00
	s_addc_u32 s89, s69, 0
	s_add_u32 s90, s68, 0x14f00
	s_addc_u32 s91, s69, 0
	s_add_u32 s92, s68, 0x15000
	s_addc_u32 s93, s69, 0
	s_add_u32 s94, s68, 0x15100
	s_addc_u32 s95, s69, 0
	s_add_u32 s72, s68, 0x15200
	v_readlane_b32 s3, v250, 0
	s_addc_u32 s73, s69, 0
	s_mul_i32 s3, s39, s3
	s_add_u32 s96, s68, 0x15300
	s_mul_i32 s3, s3, s38
	s_addc_u32 s97, s69, 0
	s_mov_b32 s52, 1
	v_mov_b32_e32 v16, 0
	s_branch .LBB0_432

.LBB0_516:
	s_waitcnt vmcnt(0)
	s_waitcnt lgkmcnt(0)
	s_barrier
	s_mov_b64 s[0:1], exec
	v_readlane_b32 s4, v250, 4
	v_readlane_b32 s5, v250, 5
	s_and_b64 s[4:5], s[0:1], s[4:5]
	s_mov_b64 exec, s[4:5]
	s_cbranch_execz .LBB0_540
	s_add_i32 s3, 0, 0x22fc0
	v_mov_b32_e32 v0, s3
	s_waitcnt vmcnt(0) expcnt(0) lgkmcnt(0)
	buffer_inv sc1
	ds_read_b32 v1, v0
	s_add_i32 s3, 0, 0x22fc4
	v_mov_b32_e32 v0, s3
	ds_read_b32 v0, v0
	s_waitcnt lgkmcnt(1)
	v_cmp_ne_u32_e32 vcc, 0, v1
	s_cbranch_vccnz .LBB0_532
	s_add_u32 s4, s68, 0x14200
	s_addc_u32 s5, s69, 0
	s_add_u32 s6, s68, 0x14400
	s_addc_u32 s7, s69, 0
	s_add_u32 s8, s68, 0x14500
	s_addc_u32 s9, s69, 0
	s_add_u32 s10, s68, 0x14600
	s_addc_u32 s11, s69, 0
	s_add_u32 s14, s68, 0x14700
	s_addc_u32 s15, s69, 0
	s_add_u32 s56, s68, 0x14800
	s_addc_u32 s57, s69, 0
	s_add_u32 s58, s68, 0x14900
	s_addc_u32 s59, s69, 0
	s_add_u32 s62, s68, 0x14a00
	s_addc_u32 s63, s69, 0
	s_add_u32 s66, s68, 0x14b00
	s_addc_u32 s67, s69, 0
	s_add_u32 s82, s68, 0x14c00
	s_addc_u32 s83, s69, 0
	s_add_u32 s84, s68, 0x14d00
	s_addc_u32 s85, s69, 0
	s_add_u32 s86, s68, 0x14e00
	s_addc_u32 s87, s69, 0
	s_add_u32 s88, s68, 0x14f00
	s_addc_u32 s89, s69, 0
	s_add_u32 s90, s68, 0x15000
	s_addc_u32 s91, s69, 0
	s_add_u32 s92, s68, 0x15100
	s_addc_u32 s93, s69, 0
	s_add_u32 s72, s68, 0x15200
	v_readlane_b32 s3, v250, 0
	s_addc_u32 s73, s69, 0
	s_mul_i32 s3, s39, s3
	s_add_u32 s94, s68, 0x15300
	s_mul_i32 s3, s3, s38
	s_addc_u32 s95, s69, 0
	s_mov_b32 s46, 1
	v_mov_b32_e32 v16, 0
	s_branch .LBB0_520

.LBB0_734:
	s_waitcnt vmcnt(0)
	s_waitcnt vmcnt(0) lgkmcnt(0)
	s_barrier
	s_mov_b64 s[0:1], exec
	v_readlane_b32 s4, v250, 4
	v_readlane_b32 s5, v250, 5
	s_and_b64 s[4:5], s[0:1], s[4:5]
	s_mov_b64 exec, s[4:5]
	s_cbranch_execz .LBB0_758
	s_add_i32 s3, 0, 0x22fc0
	v_mov_b32_e32 v0, s3
	s_waitcnt vmcnt(0) expcnt(0) lgkmcnt(0)
	buffer_inv sc1
	ds_read_b32 v1, v0
	s_add_i32 s3, 0, 0x22fc4
	v_mov_b32_e32 v0, s3
	ds_read_b32 v0, v0
	s_waitcnt lgkmcnt(1)
	v_cmp_ne_u32_e32 vcc, 0, v1
	s_cbranch_vccnz .LBB0_750
	s_add_u32 s4, s68, 0x14200
	s_addc_u32 s5, s69, 0
	s_add_u32 s6, s68, 0x14400
	s_addc_u32 s7, s69, 0
	s_add_u32 s10, s68, 0x14500
	s_addc_u32 s11, s69, 0
	s_add_u32 s20, s68, 0x14600
	s_addc_u32 s21, s69, 0
	s_add_u32 s62, s68, 0x14700
	s_addc_u32 s63, s69, 0
	s_add_u32 s66, s68, 0x14800
	s_addc_u32 s67, s69, 0
	s_add_u32 s82, s68, 0x14900
	s_addc_u32 s83, s69, 0
	s_add_u32 s84, s68, 0x14a00
	s_addc_u32 s85, s69, 0
	s_add_u32 s86, s68, 0x14b00
	s_addc_u32 s87, s69, 0
	s_add_u32 s88, s68, 0x14c00
	s_addc_u32 s89, s69, 0
	s_add_u32 s90, s68, 0x14d00
	s_addc_u32 s91, s69, 0
	s_add_u32 s92, s68, 0x14e00
	s_addc_u32 s93, s69, 0
	s_add_u32 s94, s68, 0x14f00
	s_addc_u32 s95, s69, 0
	s_add_u32 s96, s68, 0x15000
	s_addc_u32 s97, s69, 0
	s_add_u32 s72, s68, 0x15100
	s_addc_u32 s73, s69, 0
	s_add_u32 s8, s68, 0x15200
	v_readlane_b32 s3, v250, 0
	s_addc_u32 s9, s69, 0
	s_mul_i32 s3, s39, s3
	s_add_u32 s12, s68, 0x15300
	s_mul_i32 s3, s3, s38
	s_addc_u32 s13, s69, 0
	s_mov_b32 s14, 1
	v_mov_b32_e32 v16, 0
	s_branch .LBB0_738

.LBB0_882:
	s_waitcnt vmcnt(0)
	s_barrier
	s_mov_b64 s[4:5], exec
	v_readlane_b32 s2, v250, 4
	v_readlane_b32 s3, v250, 5
	s_and_b64 s[2:3], s[4:5], s[2:3]
	s_mov_b64 exec, s[2:3]
	s_cbranch_execz .LBB0_906
	s_add_i32 s2, 0, 0x22fc0
	v_mov_b32_e32 v0, s2
	s_waitcnt vmcnt(0) expcnt(0) lgkmcnt(0)
	buffer_inv sc1
	ds_read_b32 v1, v0
	s_add_i32 s2, 0, 0x22fc4
	v_mov_b32_e32 v0, s2
	ds_read_b32 v0, v0
	s_waitcnt lgkmcnt(1)
	v_cmp_ne_u32_e32 vcc, 0, v1
	s_cbranch_vccnz .LBB0_898
	s_add_u32 s6, s68, 0x14200
	s_addc_u32 s7, s69, 0
	s_add_u32 s8, s68, 0x14400
	s_addc_u32 s9, s69, 0
	s_add_u32 s10, s68, 0x14500
	s_addc_u32 s11, s69, 0
	s_add_u32 s18, s68, 0x14600
	s_addc_u32 s19, s69, 0
	s_add_u32 s20, s68, 0x14700
	s_addc_u32 s21, s69, 0
	s_add_u32 s54, s68, 0x14800
	s_addc_u32 s55, s69, 0
	s_add_u32 s56, s68, 0x14900
	s_addc_u32 s57, s69, 0
	s_add_u32 s58, s68, 0x14a00
	s_addc_u32 s59, s69, 0
	s_add_u32 s62, s68, 0x14b00
	s_addc_u32 s63, s69, 0
	s_add_u32 s66, s68, 0x14c00
	s_addc_u32 s67, s69, 0
	s_add_u32 s82, s68, 0x14d00
	s_addc_u32 s83, s69, 0
	s_add_u32 s84, s68, 0x14e00
	s_addc_u32 s85, s69, 0
	s_add_u32 s86, s68, 0x14f00
	s_addc_u32 s87, s69, 0
	s_add_u32 s88, s68, 0x15000
	s_addc_u32 s89, s69, 0
	s_add_u32 s72, s68, 0x15100
	s_addc_u32 s73, s69, 0
	s_add_u32 s90, s68, 0x15200
	v_readlane_b32 s2, v250, 0
	s_addc_u32 s91, s69, 0
	s_mul_i32 s2, s39, s2
	s_add_u32 s12, s68, 0x15300
	s_mul_i32 s2, s2, s38
	s_addc_u32 s13, s69, 0
	s_mov_b32 s3, 1
	v_mov_b32_e32 v16, 0
	s_branch .LBB0_886

.LBB0_973:
	s_waitcnt vmcnt(0)
	s_barrier
	s_mov_b64 s[0:1], exec
	v_readlane_b32 s2, v250, 4
	v_readlane_b32 s3, v250, 5
	s_and_b64 s[2:3], s[0:1], s[2:3]
	s_mov_b64 exec, s[2:3]
	s_cbranch_execz .LBB0_997
	s_add_i32 s2, 0, 0x22fc0
	v_mov_b32_e32 v0, s2
	s_waitcnt vmcnt(0) expcnt(0) lgkmcnt(0)
	buffer_inv sc1
	ds_read_b32 v1, v0
	s_add_i32 s2, 0, 0x22fc4
	v_mov_b32_e32 v0, s2
	ds_read_b32 v0, v0
	s_waitcnt lgkmcnt(1)
	v_cmp_ne_u32_e32 vcc, 0, v1
	s_cbranch_vccnz .LBB0_989
	s_add_u32 s4, s68, 0x14200
	s_addc_u32 s5, s69, 0
	s_add_u32 s8, s68, 0x14400
	s_addc_u32 s9, s69, 0
	s_add_u32 s10, s68, 0x14500
	s_addc_u32 s11, s69, 0
	s_add_u32 s16, s68, 0x14600
	s_addc_u32 s17, s69, 0
	s_add_u32 s18, s68, 0x14700
	s_addc_u32 s19, s69, 0
	s_add_u32 s20, s68, 0x14800
	s_addc_u32 s21, s69, 0
	s_add_u32 s22, s68, 0x14900
	s_addc_u32 s23, s69, 0
	s_add_u32 s24, s68, 0x14a00
	s_addc_u32 s25, s69, 0
	s_add_u32 s26, s68, 0x14b00
	s_addc_u32 s27, s69, 0
	s_add_u32 s28, s68, 0x14c00
	s_addc_u32 s29, s69, 0
	s_add_u32 s44, s68, 0x14d00
	s_addc_u32 s45, s69, 0
	s_add_u32 s48, s68, 0x14e00
	s_addc_u32 s49, s69, 0
	s_add_u32 s52, s68, 0x14f00
	s_addc_u32 s53, s69, 0
	s_add_u32 s54, s68, 0x15000
	s_addc_u32 s55, s69, 0
	s_add_u32 s56, s68, 0x15100
	s_addc_u32 s57, s69, 0
	s_add_u32 s58, s68, 0x15200
	v_readlane_b32 s2, v250, 0
	s_addc_u32 s59, s69, 0
	s_mul_i32 s2, s39, s2
	s_add_u32 s12, s68, 0x15300
	s_mul_i32 s2, s2, s38
	s_addc_u32 s13, s69, 0
	s_mov_b32 s3, 1
	v_mov_b32_e32 v16, 0
	s_branch .LBB0_977

.LBB0_1060:
	s_cmp_gt_i32 s95, 10
	s_cselect_b64 s[0:1], -1, 0
	s_and_b64 s[2:3], s[10:11], s[0:1]
	v_readlane_b32 s42, v250, 61
	s_andn2_b64 vcc, exec, s[2:3]
	v_readlane_b32 s43, v250, 62
	s_cbranch_vccnz .LBB0_1112
	s_waitcnt vmcnt(0)
	s_barrier
	s_mov_b64 s[4:5], exec
	v_readlane_b32 s2, v250, 4
	v_readlane_b32 s3, v250, 5
	s_and_b64 s[2:3], s[4:5], s[2:3]
	s_mov_b64 exec, s[2:3]
	s_cbranch_execz .LBB0_1111
	s_add_i32 s2, 0, 0x22fc0
	v_mov_b32_e32 v0, s2
	s_waitcnt vmcnt(0) expcnt(0) lgkmcnt(0)
	buffer_inv sc1
	ds_read_b32 v2, v0
	s_add_i32 s2, 0, 0x22fc4
	v_mov_b32_e32 v0, s2
	ds_read_b32 v0, v0
	s_waitcnt lgkmcnt(1)
	v_cmp_ne_u32_e32 vcc, 0, v2
	s_cbranch_vccnz .LBB0_1077
	s_add_u32 s10, s68, 0x14200
	s_addc_u32 s11, s69, 0
	s_add_u32 s16, s68, 0x14400
	s_addc_u32 s17, s69, 0
	s_add_u32 s18, s68, 0x14500
	s_addc_u32 s19, s69, 0
	s_add_u32 s20, s68, 0x14600
	s_addc_u32 s21, s69, 0
	s_add_u32 s22, s68, 0x14700
	s_addc_u32 s23, s69, 0
	s_add_u32 s24, s68, 0x14800
	s_addc_u32 s25, s69, 0
	s_add_u32 s26, s68, 0x14900
	s_addc_u32 s27, s69, 0
	s_add_u32 s28, s68, 0x14a00
	s_addc_u32 s29, s69, 0
	s_add_u32 s36, s68, 0x14b00
	s_addc_u32 s37, s69, 0
	s_add_u32 s40, s68, 0x14c00
	s_addc_u32 s41, s69, 0
	s_add_u32 s44, s68, 0x14d00
	s_addc_u32 s45, s69, 0
	s_add_u32 s46, s68, 0x14e00
	s_addc_u32 s47, s69, 0
	s_add_u32 s48, s68, 0x14f00
	s_addc_u32 s49, s69, 0
	s_add_u32 s50, s68, 0x15000
	s_addc_u32 s51, s69, 0
	s_add_u32 s52, s68, 0x15100
	s_addc_u32 s53, s69, 0
	s_add_u32 s54, s68, 0x15200
	v_readlane_b32 s2, v250, 0
	s_addc_u32 s55, s69, 0
	s_mul_i32 s2, s39, s2
	s_add_u32 s12, s68, 0x15300
	s_mul_i32 s2, s2, s38
	s_addc_u32 s13, s69, 0
	s_mov_b32 s3, 1
	v_mov_b32_e32 v16, 0
	s_branch .LBB0_1065

.LBB0_1092:
	s_or_b64 exec, exec, s[12:13]
	s_waitcnt vmcnt(0)
	s_nop 0
	s_waitcnt vmcnt(0)

.LBB0_1110:
	s_or_b64 exec, exec, s[10:11]
	s_waitcnt vmcnt(0)
	s_nop 0
	s_waitcnt vmcnt(0)

.LBB0_1129:
	s_cmp_gt_i32 s95, 11
	s_cselect_b64 s[0:1], -1, 0
	s_and_b64 s[2:3], s[4:5], s[0:1]
	s_andn2_b64 vcc, exec, s[2:3]
	s_cbranch_vccnz .LBB0_1181
	s_waitcnt vmcnt(0)
	s_barrier
	s_mov_b64 s[4:5], exec
	v_readlane_b32 s2, v250, 4
	v_readlane_b32 s3, v250, 5
	s_and_b64 s[2:3], s[4:5], s[2:3]
	s_mov_b64 exec, s[2:3]
	s_cbranch_execz .LBB0_1180
	s_add_i32 s2, 0, 0x22fc0
	v_mov_b32_e32 v0, s2
	s_waitcnt vmcnt(0) expcnt(0) lgkmcnt(0)
	buffer_inv sc1
	ds_read_b32 v2, v0
	s_add_i32 s2, 0, 0x22fc4
	v_mov_b32_e32 v0, s2
	ds_read_b32 v0, v0
	s_waitcnt lgkmcnt(1)
	v_cmp_ne_u32_e32 vcc, 0, v2
	s_cbranch_vccnz .LBB0_1146
	s_add_u32 s8, s68, 0x14200
	s_addc_u32 s9, s69, 0
	s_add_u32 s10, s68, 0x14400
	s_addc_u32 s11, s69, 0
	s_add_u32 s12, s68, 0x14500
	s_addc_u32 s13, s69, 0
	s_add_u32 s14, s68, 0x14600
	s_addc_u32 s15, s69, 0
	s_add_u32 s16, s68, 0x14700
	s_addc_u32 s17, s69, 0
	s_add_u32 s18, s68, 0x14800
	s_addc_u32 s19, s69, 0
	s_add_u32 s20, s68, 0x14900
	s_addc_u32 s21, s69, 0
	s_add_u32 s22, s68, 0x14a00
	s_addc_u32 s23, s69, 0
	s_add_u32 s24, s68, 0x14b00
	s_addc_u32 s25, s69, 0
	s_add_u32 s26, s68, 0x14c00
	s_addc_u32 s27, s69, 0
	s_add_u32 s28, s68, 0x14d00
	s_addc_u32 s29, s69, 0
	s_add_u32 s36, s68, 0x14e00
	s_addc_u32 s37, s69, 0
	s_add_u32 s40, s68, 0x14f00
	s_addc_u32 s41, s69, 0
	s_add_u32 s42, s68, 0x15000
	s_addc_u32 s43, s69, 0
	s_add_u32 s44, s68, 0x15100
	s_addc_u32 s45, s69, 0
	s_add_u32 s46, s68, 0x15200
	v_readlane_b32 s2, v250, 0
	s_addc_u32 s47, s69, 0
	s_mul_i32 s2, s39, s2
	s_add_u32 s48, s68, 0x15300
	s_mul_i32 s2, s2, s38
	s_addc_u32 s49, s69, 0
	s_mov_b32 s3, 1
	v_mov_b32_e32 v16, 0
	s_branch .LBB0_1134

.LBB0_1179:
	s_or_b64 exec, exec, s[8:9]
	s_waitcnt vmcnt(0)
	s_nop 0
	s_waitcnt vmcnt(0)
